# safe variant 2: baseline GEMMs; conv rewrite + phase0 adaLN/CM load batching + first-barrier census load batching
# baseline (speedup 1.0000x reference)
.LBB0_85:
	v_readlane_b32 s6, v253, 19
	v_readlane_b32 s7, v253, 20
	v_readlane_b32 s5, v253, 13
	s_mov_b64 s[8:9], -1
	s_mov_b64 s[20:21], -1
	s_waitcnt lgkmcnt(0)
	s_nop 0
	global_load_dword v0, v16, s[6:7] sc1
	v_readlane_b32 s6, v253, 27
	v_readlane_b32 s7, v253, 28
	s_nop 4
	global_load_dword v1, v16, s[6:7] sc1
	v_readlane_b32 s6, v253, 29
	v_readlane_b32 s7, v253, 30
	s_nop 4
	global_load_dword v2, v16, s[6:7] sc1
	v_readlane_b32 s6, v253, 15
	v_readlane_b32 s7, v253, 16
	s_nop 4
	global_load_dword v3, v16, s[6:7] sc1
	v_readlane_b32 s6, v253, 17
	v_readlane_b32 s7, v253, 18
	s_nop 4
	global_load_dword v4, v16, s[6:7] sc1
	v_readlane_b32 s6, v253, 21
	v_readlane_b32 s7, v253, 22
	s_nop 4
	global_load_dword v5, v16, s[6:7] sc1
	v_readlane_b32 s6, v253, 23
	v_readlane_b32 s7, v253, 24
	s_nop 4
	global_load_dword v6, v16, s[6:7] sc1
	v_readlane_b32 s6, v253, 25
	v_readlane_b32 s7, v253, 26
	s_nop 4
	global_load_dword v7, v16, s[6:7] sc1
	v_readlane_b32 s6, v253, 31
	v_readlane_b32 s7, v253, 32
	s_nop 4
	global_load_dword v8, v16, s[6:7] sc1
	v_readlane_b32 s6, v252, 55
	v_readlane_b32 s7, v252, 56
	s_nop 4
	global_load_dword v9, v16, s[6:7] sc1
	v_readlane_b32 s6, v253, 35
	v_readlane_b32 s7, v253, 36
	s_nop 4
	global_load_dword v10, v16, s[6:7] sc1
	v_readlane_b32 s6, v253, 37
	v_readlane_b32 s7, v253, 38
	s_nop 4
	global_load_dword v11, v16, s[6:7] sc1
	v_readlane_b32 s6, v253, 39
	v_readlane_b32 s7, v253, 40
	s_nop 4
	global_load_dword v12, v16, s[6:7] sc1
	v_readlane_b32 s6, v253, 41
	v_readlane_b32 s7, v253, 42
	s_nop 4
	global_load_dword v13, v16, s[6:7] sc1
	v_readlane_b32 s6, v253, 43
	v_readlane_b32 s7, v253, 44
	s_nop 4
	global_load_dword v14, v16, s[6:7] sc1
	v_readlane_b32 s6, v253, 45
	v_readlane_b32 s7, v253, 46
	s_nop 4
	global_load_dword v15, v16, s[6:7] sc1
	s_waitcnt vmcnt(0)
	v_add_u32_e32 v17, v1, v0
	v_add_u32_e32 v17, v17, v2
	v_add_u32_e32 v17, v17, v3
	v_add_u32_e32 v17, v17, v4
	v_add_u32_e32 v17, v17, v5
	v_add_u32_e32 v17, v17, v6
	v_add_u32_e32 v17, v17, v7
	v_add_u32_e32 v17, v17, v8
	v_add_u32_e32 v17, v17, v9
	v_add_u32_e32 v17, v17, v10
	v_add_u32_e32 v17, v17, v11
	v_add_u32_e32 v17, v17, v12
	v_add_u32_e32 v17, v17, v13
	v_add_u32_e32 v17, v17, v14
	v_add_u32_e32 v17, v17, v15
	v_cmp_eq_u32_e32 vcc, s5, v17
	s_cbranch_vccnz .LBB0_84
	s_and_b32 s5, s4, 0xff
	s_cmp_eq_u32 s5, 0
	s_mov_b64 s[22:23], -1
	s_sleep 1
	s_cbranch_scc1 .LBB0_89
	s_and_b64 vcc, exec, s[22:23]
	s_cbranch_vccz .LBB0_84
